# code placement: the 14 GEMM K-loop heads aligned to 64 bytes (.p2align 6); on top of v67
# speedup vs baseline: 1.0028x; 1.0014x over previous
;     ...
;         if (!cur.keep) {
; #pragma unroll
;             for (int a = 0; a < 2; ++a)
; #pragma unroll
;                 for (int b = 0; b < 2; ++b)
; #pragma unroll
;                     for (int m = 0; m < 4; ++m)
; #pragma unroll
;                         for (int n = 0; n < 2; ++n) { f32x2 z0, z1; asm("v_mov_b64 %0, 0\n\tv_mov_b64 %1, 0" : "=v"(z0), "=v"(z1));
;                     acc[a][b][m][n] = __builtin_shufflevector(z0, z1, 0, 1, 2, 3); }
;         }
;         cur = nxt; cA = nA; cB = nB; ++ui;
.LBB0_222:
	s_lshl_b32 s28, s27, 20
	s_and_b64 s[30:31], s[38:39], exec
	s_cselect_b32 s30, s28, s50
	s_lshl_b32 s29, s26, 20
	s_and_b64 s[52:53], s[38:39], exec
	v_mov_b64_e32 v[12:13], v[4:5]
	v_mov_b64_e32 v[20:21], v[4:5]
	s_waitcnt vmcnt(15)
	v_mov_b64_e32 v[28:29], v[4:5]
	v_mov_b64_e32 v[36:37], v[4:5]
	v_mov_b64_e32 v[44:45], v[4:5]
	v_mov_b64_e32 v[52:53], v[4:5]
	v_mov_b64_e32 v[60:61], v[4:5]
	v_mov_b64_e32 v[8:9], v[4:5]
	v_mov_b64_e32 v[16:17], v[4:5]
	v_mov_b64_e32 v[24:25], v[4:5]
	v_mov_b64_e32 v[32:33], v[4:5]
	v_mov_b64_e32 v[40:41], v[4:5]
	v_mov_b64_e32 v[48:49], v[4:5]
	v_mov_b64_e32 v[56:57], v[4:5]
	v_mov_b64_e32 v[64:65], v[4:5]
	v_mov_b64_e32 v[68:69], v[4:5]
	v_mov_b64_e32 v[76:77], v[4:5]
	v_mov_b64_e32 v[92:93], v[4:5]
	v_mov_b64_e32 v[108:109], v[4:5]
	v_mov_b64_e32 v[116:117], v[4:5]
	v_mov_b64_e32 v[124:125], v[4:5]
	v_mov_b64_e32 v[132:133], v[4:5]
	v_mov_b64_e32 v[140:141], v[4:5]
	v_mov_b64_e32 v[72:73], v[4:5]
	v_mov_b64_e32 v[80:81], v[4:5]
	v_mov_b64_e32 v[96:97], v[4:5]
	v_mov_b64_e32 v[112:113], v[4:5]
	v_mov_b64_e32 v[120:121], v[4:5]
	v_mov_b64_e32 v[128:129], v[4:5]
	v_mov_b64_e32 v[136:137], v[4:5]
	v_mov_b64_e32 v[144:145], v[4:5]
	s_cselect_b32 s31, s29, s42
	s_add_i32 s50, s50, 0x80080
	s_add_i32 s51, s42, 0x100
	s_mov_b32 s52, -2
	v_mov_b64_e32 v[10:11], v[2:3]
	v_mov_b64_e32 v[18:19], v[2:3]
	v_mov_b64_e32 v[26:27], v[2:3]
	v_mov_b64_e32 v[34:35], v[2:3]
	v_mov_b64_e32 v[42:43], v[2:3]
	v_mov_b64_e32 v[50:51], v[2:3]
	v_mov_b64_e32 v[58:59], v[2:3]
	v_mov_b64_e32 v[6:7], v[2:3]
	v_mov_b64_e32 v[14:15], v[2:3]
	v_mov_b64_e32 v[22:23], v[2:3]
	v_mov_b64_e32 v[30:31], v[2:3]
	v_mov_b64_e32 v[38:39], v[2:3]
	v_mov_b64_e32 v[46:47], v[2:3]
	v_mov_b64_e32 v[54:55], v[2:3]
	v_mov_b64_e32 v[62:63], v[2:3]
	v_mov_b64_e32 v[66:67], v[2:3]
	v_mov_b64_e32 v[74:75], v[2:3]
	v_mov_b64_e32 v[90:91], v[2:3]
	v_mov_b64_e32 v[106:107], v[2:3]
	v_mov_b64_e32 v[114:115], v[2:3]
	v_mov_b64_e32 v[122:123], v[2:3]
	v_mov_b64_e32 v[130:131], v[2:3]
	v_mov_b64_e32 v[138:139], v[2:3]
	v_mov_b64_e32 v[70:71], v[2:3]
	v_mov_b64_e32 v[78:79], v[2:3]
	v_mov_b64_e32 v[94:95], v[2:3]
	v_mov_b64_e32 v[110:111], v[2:3]
	v_mov_b64_e32 v[118:119], v[2:3]
	v_mov_b64_e32 v[126:127], v[2:3]
	v_mov_b64_e32 v[134:135], v[2:3]
	v_mov_b64_e32 v[142:143], v[2:3]
	.p2align	6

; #define PG8_STAGEX(rs, bufoff, soff, voff) do { _Pragma("unroll") for (int _i = 0; _i < 2; ++_i) \
;         __builtin_amdgcn_raw_ptr_buffer_load_lds(rs, (LAS unsigned*)(lds + (bufoff) + ldsw + _i * 8192), 16, (voff)[_i], (soff), 0, 0); } while (0)
; #define PG8_WAIT_V(n) asm volatile("s_waitcnt vmcnt(" #n ")" ::: "memory")
; #define PG8_BAR __builtin_amdgcn_s_barrier()
;     ...
;     const int aoff = lds_byte(wr * 64 + fr, fq * 8), boff = lds_byte(wc * 32 + fr, fq * 8);
;     ...
;     Unit cur, nxt; int ui = 0;
;     if constexpr (QV == 2) { if (!S.next_tail(0, cur)) return; } else { if (!S.next(0, cur)) return; }
;     f32x4 acc[2][2][4][2];
; #pragma unroll
;     for (int a = 0; a < 2; ++a)
; #pragma unroll
;         for (int b = 0; b < 2; ++b)
; #pragma unroll
;             for (int m = 0; m < 4; ++m)
; #pragma unroll
;                 for (int n = 0; n < 2; ++n) { f32x2 z0, z1; asm("v_mov_b64 %0, 0\n\tv_mov_b64 %1, 0" : "=v"(z0), "=v"(z1));
;                     acc[a][b][m][n] = __builtin_shufflevector(z0, z1, 0, 1, 2, 3); }
;     bf16x8 At[4][2], B0[2][2], B1[2][2];
;     unsigned cA = (unsigned)cur.pm * tstepA + cur.aoff, cB = (unsigned)cur.pn * tstepB + cur.boff;
;     PG8_STAGEX(rsB, PG8_SB(0, 0), cB, voffB); PG8_STAGEX(rsB, PG8_SB(0, 1), cB + hstepB, voffB); PG8_STAGEX(rsA, PG8_SA(0, 0), cA, voffA); PG8_STAGEX(rsA, PG8_SA(0, 1), cA + hstepA, voffA);
;     if (wr == 1) PG8_BAR;
;     PG8_WAIT_V(2); PG8_BAR;
;     PG8_STAGEX(rsB, PG8_SB(1, 0), cB + kstep, voffB); PG8_STAGEX(rsA, PG8_SA(1, 0), cA + kstep, voffA); PG8_STAGEX(rsB, PG8_SB(1, 1), cB + hstepB + kstep, voffB);
;     PG8_WAIT_V(6); PG8_BAR;
.LBB0_239:
	v_lshrrev_b32_e32 v7, 1, v149
	v_and_b32_e32 v71, 24, v7
	v_and_b32_e32 v6, 15, v149
	v_lshlrev_b32_e32 v7, 1, v71
	v_lshl_or_b32 v70, s19, 6, v6
	v_lshl_or_b32 v6, v6, 6, v7
	v_lshlrev_b32_e32 v7, 2, v149
	s_lshl_b32 s19, s19, 13
	v_and_b32_e32 v7, 32, v7
	v_bitop3_b32 v8, v6, s19, v7 bitop3:0xde
	s_lshl_b32 s19, s20, 5
	s_and_b32 s19, s19, 0x60
	s_lshl_b32 s20, s19, 7
	v_bitop3_b32 v6, s20, v6, v7 bitop3:0xf6
	s_add_i32 s20, s12, 0x18000
	s_or_b32 s22, s11, 0x80
	s_mov_b32 m0, s20
	s_add_i32 s21, s12, 0x1a000
	s_waitcnt vmcnt(2)
	s_barrier
	buffer_load_dwordx4 v67, s[40:43], s22 offen lds
	s_mov_b32 m0, s21
	s_or_b32 s24, s17, 0x80
	buffer_load_dwordx4 v69, s[40:43], s22 offen lds
	s_add_i32 s22, s12, 0x8000
	s_mov_b32 m0, s22
	s_add_i32 s23, s12, 0xa000
	buffer_load_dwordx4 v66, s[76:79], s24 offen lds
	s_mov_b32 m0, s23
	s_or_b32 s26, s11, 0x80080
	buffer_load_dwordx4 v68, s[76:79], s24 offen lds
	s_add_i32 s24, s12, 0x1c000
	s_mov_b32 m0, s24
	s_add_i32 s25, s12, 0x1e000
	buffer_load_dwordx4 v67, s[40:43], s26 offen lds
	s_mov_b32 m0, s25
	s_sext_i32_i16 s9, s9
	buffer_load_dwordx4 v69, s[40:43], s26 offen lds
	s_waitcnt vmcnt(6)
	s_movk_i32 s26, 0x100
	s_mov_b32 s27, -2
	v_add_u32_e32 v72, 0, v6
	v_add_u32_e32 v73, 0, v8
	v_mov_b32_e32 v10, v2
	v_mov_b32_e32 v11, v3
	v_mov_b32_e32 v12, v4
	v_mov_b32_e32 v13, v5
	v_mov_b32_e32 v18, v2
	v_mov_b32_e32 v19, v3
	v_mov_b32_e32 v20, v4
	v_mov_b32_e32 v21, v5
	s_waitcnt vmcnt(15)
	v_mov_b32_e32 v26, v2
	v_mov_b32_e32 v27, v3
	v_mov_b32_e32 v28, v4
	v_mov_b32_e32 v29, v5
	v_mov_b32_e32 v34, v2
	v_mov_b32_e32 v35, v3
	v_mov_b32_e32 v36, v4
	v_mov_b32_e32 v37, v5
	v_mov_b32_e32 v42, v2
	v_mov_b32_e32 v43, v3
	v_mov_b32_e32 v44, v4
	v_mov_b32_e32 v45, v5
	v_mov_b32_e32 v46, v2
	v_mov_b32_e32 v47, v3
	v_mov_b32_e32 v48, v4
	v_mov_b32_e32 v49, v5
	v_mov_b32_e32 v50, v2
	v_mov_b32_e32 v51, v3
	v_mov_b32_e32 v52, v4
	v_mov_b32_e32 v53, v5
	v_mov_b32_e32 v6, v2
	v_mov_b32_e32 v7, v3
	v_mov_b32_e32 v8, v4
	v_mov_b32_e32 v9, v5
	v_mov_b32_e32 v14, v2
	v_mov_b32_e32 v15, v3
	v_mov_b32_e32 v16, v4
	v_mov_b32_e32 v17, v5
	v_mov_b32_e32 v22, v2
	v_mov_b32_e32 v23, v3
	v_mov_b32_e32 v24, v4
	v_mov_b32_e32 v25, v5
	v_mov_b32_e32 v30, v2
	v_mov_b32_e32 v31, v3
	v_mov_b32_e32 v32, v4
	v_mov_b32_e32 v33, v5
	v_mov_b32_e32 v38, v2
	v_mov_b32_e32 v39, v3
	v_mov_b32_e32 v40, v4
	v_mov_b32_e32 v41, v5
	v_mov_b32_e32 v54, v2
	v_mov_b32_e32 v55, v3
	v_mov_b32_e32 v56, v4
	v_mov_b32_e32 v57, v5
	v_mov_b32_e32 v58, v2
	v_mov_b32_e32 v59, v3
	v_mov_b32_e32 v60, v4
	v_mov_b32_e32 v61, v5
	v_mov_b32_e32 v62, v2
	v_mov_b32_e32 v63, v3
	v_mov_b32_e32 v64, v4
	v_mov_b32_e32 v65, v5
	s_barrier
	.p2align	6

;     ...
;         if (!cur.keep) {
; #pragma unroll
;             for (int a = 0; a < 2; ++a)
; #pragma unroll
;                 for (int b = 0; b < 2; ++b)
; #pragma unroll
;                     for (int m = 0; m < 4; ++m)
; #pragma unroll
;                         for (int n = 0; n < 2; ++n) { f32x2 z0, z1; asm("v_mov_b64 %0, 0\n\tv_mov_b64 %1, 0" : "=v"(z0), "=v"(z1));
;                     acc[a][b][m][n] = __builtin_shufflevector(z0, z1, 0, 1, 2, 3); }
;         }
;         cur = nxt; cA = nA; cB = nB; ++ui;
.LBB0_322:
	s_mul_i32 s74, s58, 0x2b0000
	s_and_b64 s[30:31], s[52:53], exec
	s_mul_i32 s75, s43, 0x2b0000
	s_waitcnt lgkmcnt(0)
	v_mov_b64_e32 v[8:9], v[4:5]
	v_mov_b64_e32 v[12:13], v[4:5]
	v_mov_b64_e32 v[16:17], v[4:5]
	v_mov_b64_e32 v[20:21], v[4:5]
	v_mov_b64_e32 v[24:25], v[4:5]
	s_waitcnt vmcnt(15)
	v_mov_b64_e32 v[28:29], v[4:5]
	v_mov_b64_e32 v[32:33], v[4:5]
	v_mov_b64_e32 v[68:69], v[4:5]
	v_mov_b64_e32 v[72:73], v[4:5]
	v_mov_b64_e32 v[76:77], v[4:5]
	v_mov_b64_e32 v[80:81], v[4:5]
	v_mov_b64_e32 v[84:85], v[4:5]
	v_mov_b64_e32 v[88:89], v[4:5]
	v_mov_b64_e32 v[92:93], v[4:5]
	v_mov_b64_e32 v[96:97], v[4:5]
	v_mov_b64_e32 v[36:37], v[4:5]
	v_mov_b64_e32 v[40:41], v[4:5]
	v_mov_b64_e32 v[44:45], v[4:5]
	v_mov_b64_e32 v[48:49], v[4:5]
	v_mov_b64_e32 v[52:53], v[4:5]
	v_mov_b64_e32 v[56:57], v[4:5]
	v_mov_b64_e32 v[60:61], v[4:5]
	v_mov_b64_e32 v[64:65], v[4:5]
	v_mov_b64_e32 v[100:101], v[4:5]
	v_mov_b64_e32 v[104:105], v[4:5]
	v_mov_b64_e32 v[128:129], v[4:5]
	v_mov_b64_e32 v[132:133], v[4:5]
	v_mov_b64_e32 v[140:141], v[4:5]
	v_mov_b64_e32 v[144:145], v[4:5]
	v_mov_b64_e32 v[148:149], v[4:5]
	v_mov_b64_e32 v[152:153], v[4:5]
	s_mov_b32 s73, s58
	s_mov_b32 s72, s43
	s_cselect_b32 s30, s74, s51
	s_cselect_b32 s31, s75, s57
	s_add_i32 s51, s51, 0x158080
	s_addk_i32 s57, 0x100
	s_mov_b32 s58, -2
	v_mov_b64_e32 v[6:7], v[2:3]
	v_mov_b64_e32 v[10:11], v[2:3]
	v_mov_b64_e32 v[14:15], v[2:3]
	v_mov_b64_e32 v[18:19], v[2:3]
	v_mov_b64_e32 v[22:23], v[2:3]
	v_mov_b64_e32 v[26:27], v[2:3]
	v_mov_b64_e32 v[30:31], v[2:3]
	v_mov_b64_e32 v[66:67], v[2:3]
	v_mov_b64_e32 v[70:71], v[2:3]
	v_mov_b64_e32 v[74:75], v[2:3]
	v_mov_b64_e32 v[78:79], v[2:3]
	v_mov_b64_e32 v[82:83], v[2:3]
	v_mov_b64_e32 v[86:87], v[2:3]
	v_mov_b64_e32 v[90:91], v[2:3]
	v_mov_b64_e32 v[94:95], v[2:3]
	v_mov_b64_e32 v[34:35], v[2:3]
	v_mov_b64_e32 v[38:39], v[2:3]
	v_mov_b64_e32 v[42:43], v[2:3]
	v_mov_b64_e32 v[46:47], v[2:3]
	v_mov_b64_e32 v[50:51], v[2:3]
	v_mov_b64_e32 v[54:55], v[2:3]
	v_mov_b64_e32 v[58:59], v[2:3]
	v_mov_b64_e32 v[62:63], v[2:3]
	v_mov_b64_e32 v[98:99], v[2:3]
	v_mov_b64_e32 v[102:103], v[2:3]
	v_mov_b64_e32 v[126:127], v[2:3]
	v_mov_b64_e32 v[130:131], v[2:3]
	v_mov_b64_e32 v[138:139], v[2:3]
	v_mov_b64_e32 v[142:143], v[2:3]
	v_mov_b64_e32 v[146:147], v[2:3]
	v_mov_b64_e32 v[150:151], v[2:3]
	.p2align	6

;     ...
;         if (!cur.keep) {
; #pragma unroll
;             for (int a = 0; a < 2; ++a)
; #pragma unroll
;                 for (int b = 0; b < 2; ++b)
; #pragma unroll
;                     for (int m = 0; m < 4; ++m)
; #pragma unroll
;                         for (int n = 0; n < 2; ++n) { f32x2 z0, z1; asm("v_mov_b64 %0, 0\n\tv_mov_b64 %1, 0" : "=v"(z0), "=v"(z1));
;                     acc[a][b][m][n] = __builtin_shufflevector(z0, z1, 0, 1, 2, 3); }
;         }
;         cur = nxt; cA = nA; cB = nB; ++ui;
.LBB0_436:
	s_lshl_b32 s26, s25, 20
	s_and_b64 s[30:31], s[48:49], exec
	s_cselect_b32 s2, s26, s7
	s_lshl_b32 s27, s24, 20
	s_and_b64 s[30:31], s[48:49], exec
	s_waitcnt vmcnt(15)
	v_mov_b64_e32 v[28:29], v[8:9]
	v_mov_b64_e32 v[2:3], v[6:7]
	v_mov_b64_e32 v[20:21], v[8:9]
	v_mov_b64_e32 v[12:13], v[8:9]
	v_mov_b64_e32 v[24:25], v[8:9]
	v_mov_b64_e32 v[16:17], v[8:9]
	v_mov_b64_e32 v[32:33], v[8:9]
	v_mov_b64_e32 v[76:77], v[8:9]
	v_mov_b64_e32 v[92:93], v[8:9]
	v_mov_b64_e32 v[68:69], v[8:9]
	v_mov_b64_e32 v[84:85], v[8:9]
	v_mov_b64_e32 v[72:73], v[8:9]
	v_mov_b64_e32 v[88:89], v[8:9]
	v_mov_b64_e32 v[80:81], v[8:9]
	v_mov_b64_e32 v[96:97], v[8:9]
	v_mov_b64_e32 v[44:45], v[8:9]
	v_mov_b64_e32 v[60:61], v[8:9]
	v_mov_b64_e32 v[36:37], v[8:9]
	v_mov_b64_e32 v[52:53], v[8:9]
	v_mov_b64_e32 v[40:41], v[8:9]
	v_mov_b64_e32 v[56:57], v[8:9]
	v_mov_b64_e32 v[48:49], v[8:9]
	v_mov_b64_e32 v[64:65], v[8:9]
	v_mov_b64_e32 v[108:109], v[8:9]
	v_mov_b64_e32 v[124:125], v[8:9]
	v_mov_b64_e32 v[100:101], v[8:9]
	v_mov_b64_e32 v[116:117], v[8:9]
	v_mov_b64_e32 v[104:105], v[8:9]
	v_mov_b64_e32 v[120:121], v[8:9]
	v_mov_b64_e32 v[112:113], v[8:9]
	v_mov_b64_e32 v[128:129], v[8:9]
	s_cselect_b32 s5, s27, s28
	s_add_i32 s7, s7, 0x80080
	s_addk_i32 s28, 0x100
	s_mov_b32 s29, -2
	v_mov_b64_e32 v[26:27], v[6:7]
	v_mov_b64_e32 v[4:5], v[8:9]
	v_mov_b64_e32 v[18:19], v[6:7]
	v_mov_b64_e32 v[10:11], v[6:7]
	v_mov_b64_e32 v[22:23], v[6:7]
	v_mov_b64_e32 v[14:15], v[6:7]
	v_mov_b64_e32 v[30:31], v[6:7]
	v_mov_b64_e32 v[74:75], v[6:7]
	v_mov_b64_e32 v[90:91], v[6:7]
	v_mov_b64_e32 v[66:67], v[6:7]
	v_mov_b64_e32 v[82:83], v[6:7]
	v_mov_b64_e32 v[70:71], v[6:7]
	v_mov_b64_e32 v[86:87], v[6:7]
	v_mov_b64_e32 v[78:79], v[6:7]
	v_mov_b64_e32 v[94:95], v[6:7]
	v_mov_b64_e32 v[42:43], v[6:7]
	v_mov_b64_e32 v[58:59], v[6:7]
	v_mov_b64_e32 v[34:35], v[6:7]
	v_mov_b64_e32 v[50:51], v[6:7]
	v_mov_b64_e32 v[38:39], v[6:7]
	v_mov_b64_e32 v[54:55], v[6:7]
	v_mov_b64_e32 v[46:47], v[6:7]
	v_mov_b64_e32 v[62:63], v[6:7]
	v_mov_b64_e32 v[106:107], v[6:7]
	v_mov_b64_e32 v[122:123], v[6:7]
	v_mov_b64_e32 v[98:99], v[6:7]
	v_mov_b64_e32 v[114:115], v[6:7]
	v_mov_b64_e32 v[102:103], v[6:7]
	v_mov_b64_e32 v[118:119], v[6:7]
	v_mov_b64_e32 v[110:111], v[6:7]
	v_mov_b64_e32 v[126:127], v[6:7]
	.p2align	6

; #define PG8_STAGEX(rs, bufoff, soff, voff) do { _Pragma("unroll") for (int _i = 0; _i < 2; ++_i) \
;         __builtin_amdgcn_raw_ptr_buffer_load_lds(rs, (LAS unsigned*)(lds + (bufoff) + ldsw + _i * 8192), 16, (voff)[_i], (soff), 0, 0); } while (0)
; #define PG8_WAIT_V(n) asm volatile("s_waitcnt vmcnt(" #n ")" ::: "memory")
; #define PG8_BAR __builtin_amdgcn_s_barrier()
;     ...
;     const int aoff = lds_byte(wr * 64 + fr, fq * 8), boff = lds_byte(wc * 32 + fr, fq * 8);
;     ...
;     Unit cur, nxt; int ui = 0;
;     if constexpr (QV == 2) { if (!S.next_tail(0, cur)) return; } else { if (!S.next(0, cur)) return; }
;     f32x4 acc[2][2][4][2];
; #pragma unroll
;     for (int a = 0; a < 2; ++a)
; #pragma unroll
;         for (int b = 0; b < 2; ++b)
; #pragma unroll
;             for (int m = 0; m < 4; ++m)
; #pragma unroll
;                 for (int n = 0; n < 2; ++n) { f32x2 z0, z1; asm("v_mov_b64 %0, 0\n\tv_mov_b64 %1, 0" : "=v"(z0), "=v"(z1));
;                     acc[a][b][m][n] = __builtin_shufflevector(z0, z1, 0, 1, 2, 3); }
;     bf16x8 At[4][2], B0[2][2], B1[2][2];
;     unsigned cA = (unsigned)cur.pm * tstepA + cur.aoff, cB = (unsigned)cur.pn * tstepB + cur.boff;
;     PG8_STAGEX(rsB, PG8_SB(0, 0), cB, voffB); PG8_STAGEX(rsB, PG8_SB(0, 1), cB + hstepB, voffB); PG8_STAGEX(rsA, PG8_SA(0, 0), cA, voffA); PG8_STAGEX(rsA, PG8_SA(0, 1), cA + hstepA, voffA);
;     if (wr == 1) PG8_BAR;
;     PG8_WAIT_V(2); PG8_BAR;
;     PG8_STAGEX(rsB, PG8_SB(1, 0), cB + kstep, voffB); PG8_STAGEX(rsA, PG8_SA(1, 0), cA + kstep, voffA); PG8_STAGEX(rsB, PG8_SB(1, 1), cB + hstepB + kstep, voffB);
;     PG8_WAIT_V(6); PG8_BAR;
.LBB0_541:
	s_add_i32 s19, s11, 0x18000
	s_lshr_b32 s16, s9, 2
	s_or_b32 s9, s10, 0x80
	s_mov_b32 m0, s19
	s_add_i32 s20, s11, 0x1a000
	s_waitcnt vmcnt(2)
	s_barrier
	buffer_load_dwordx4 v67, s[56:59], s9 offen lds
	s_mov_b32 m0, s20
	s_add_i32 s21, s11, 0x8000
	buffer_load_dwordx4 v69, s[56:59], s9 offen lds
	s_or_b32 s9, s17, 0x80
	s_mov_b32 m0, s21
	s_add_i32 s22, s11, 0xa000
	buffer_load_dwordx4 v66, s[76:79], s9 offen lds
	s_mov_b32 m0, s22
	s_add_i32 s23, s11, 0x1c000
	buffer_load_dwordx4 v68, s[76:79], s9 offen lds
	s_or_b32 s9, s10, 0x80080
	s_mov_b32 m0, s23
	s_add_i32 s24, s11, 0x1e000
	buffer_load_dwordx4 v67, s[56:59], s9 offen lds
	s_mov_b32 m0, s24
	v_lshrrev_b32_e32 v2, 1, v177
	buffer_load_dwordx4 v69, s[56:59], s9 offen lds
	v_and_b32_e32 v109, 24, v2
	v_and_b32_e32 v105, 15, v177
	v_lshlrev_b32_e32 v2, 1, v109
	v_lshlrev_b32_e32 v3, 2, v177
	s_and_b32 s2, s2, 3
	s_lshl_b32 s9, s25, 6
	v_lshl_or_b32 v2, v105, 6, v2
	s_lshl_b32 s25, s25, 13
	v_and_b32_e32 v3, 32, v3
	v_bitop3_b32 v4, v2, s25, v3 bitop3:0xde
	s_lshl_b32 s25, s2, 12
	s_waitcnt vmcnt(6)
	v_bitop3_b32 v2, v2, s25, v3 bitop3:0xde
	v_or_b32_e32 v70, s9, v105
	s_movk_i32 s25, 0x100
	s_mov_b32 s26, -2
	v_add_u32_e32 v71, 0, v2
	v_add_u32_e32 v72, 0, v4
	s_waitcnt vmcnt(15)
	v_mov_b32_e32 v26, v6
	v_mov_b32_e32 v27, v7
	v_mov_b32_e32 v28, v8
	v_mov_b32_e32 v29, v9
	v_mov_b32_e32 v2, v6
	v_mov_b32_e32 v3, v7
	v_mov_b32_e32 v4, v8
	v_mov_b32_e32 v5, v9
	v_mov_b32_e32 v18, v6
	v_mov_b32_e32 v19, v7
	v_mov_b32_e32 v20, v8
	v_mov_b32_e32 v21, v9
	v_mov_b32_e32 v10, v6
	v_mov_b32_e32 v11, v7
	v_mov_b32_e32 v12, v8
	v_mov_b32_e32 v13, v9
	v_mov_b32_e32 v22, v6
	v_mov_b32_e32 v23, v7
	v_mov_b32_e32 v24, v8
	v_mov_b32_e32 v25, v9
	v_mov_b32_e32 v14, v6
	v_mov_b32_e32 v15, v7
	v_mov_b32_e32 v16, v8
	v_mov_b32_e32 v17, v9
	v_mov_b32_e32 v30, v6
	v_mov_b32_e32 v31, v7
	v_mov_b32_e32 v32, v8
	v_mov_b32_e32 v33, v9
	v_mov_b32_e32 v42, v6
	v_mov_b32_e32 v43, v7
	v_mov_b32_e32 v44, v8
	v_mov_b32_e32 v45, v9
	v_mov_b32_e32 v58, v6
	v_mov_b32_e32 v59, v7
	v_mov_b32_e32 v60, v8
	v_mov_b32_e32 v61, v9
	v_mov_b32_e32 v34, v6
	v_mov_b32_e32 v35, v7
	v_mov_b32_e32 v36, v8
	v_mov_b32_e32 v37, v9
	v_mov_b32_e32 v50, v6
	v_mov_b32_e32 v51, v7
	v_mov_b32_e32 v52, v8
	v_mov_b32_e32 v53, v9
	v_mov_b32_e32 v38, v6
	v_mov_b32_e32 v39, v7
	v_mov_b32_e32 v40, v8
	v_mov_b32_e32 v41, v9
	v_mov_b32_e32 v54, v6
	v_mov_b32_e32 v55, v7
	v_mov_b32_e32 v56, v8
	v_mov_b32_e32 v57, v9
	v_mov_b32_e32 v46, v6
	v_mov_b32_e32 v47, v7
	v_mov_b32_e32 v48, v8
	v_mov_b32_e32 v49, v9
	v_mov_b32_e32 v62, v6
	v_mov_b32_e32 v63, v7
	v_mov_b32_e32 v64, v8
	v_mov_b32_e32 v65, v9
	s_barrier
	.p2align	6

;     ...
;         bool has_next; if constexpr (QV == 2) has_next = S.next_tail(ui + 1, nxt); else has_next = S.next(ui + 1, nxt);
;         const unsigned nA = has_next ? (unsigned)nxt.pm * tstepA + nxt.aoff : cA, nB = has_next ? (unsigned)nxt.pn * tstepB + nxt.boff : cB;
;     ...
;         if (!cur.keep) {
; #pragma unroll
;             for (int a = 0; a < 2; ++a)
; #pragma unroll
;                 for (int b = 0; b < 2; ++b)
; #pragma unroll
;                     for (int m = 0; m < 4; ++m)
; #pragma unroll
;                         for (int n = 0; n < 2; ++n) { f32x2 z0, z1; asm("v_mov_b64 %0, 0\n\tv_mov_b64 %1, 0" : "=v"(z0), "=v"(z1));
;                     acc[a][b][m][n] = __builtin_shufflevector(z0, z1, 0, 1, 2, 3); }
;         }
;         cur = nxt; cA = nA; cB = nB; ++ui;
.LBB0_786:
	s_lshl_b32 s92, s3, 19
	s_add_i32 s92, s92, s2
	s_andn2_b64 vcc, exec, s[58:59]
	s_lshl_b32 s5, s8, 16
	s_cbranch_vccnz .LBB0_882
	s_and_b64 s[30:31], s[44:45], exec
	v_mov_b64_e32 v[68:69], v[4:5]
	v_mov_b64_e32 v[12:13], v[4:5]
	v_mov_b64_e32 v[76:77], v[4:5]
	v_mov_b64_e32 v[20:21], v[4:5]
	v_mov_b64_e32 v[84:85], v[4:5]
	s_waitcnt vmcnt(15)
	v_mov_b64_e32 v[28:29], v[4:5]
	v_mov_b64_e32 v[92:93], v[4:5]
	v_mov_b64_e32 v[8:9], v[4:5]
	v_mov_b64_e32 v[72:73], v[4:5]
	v_mov_b64_e32 v[16:17], v[4:5]
	v_mov_b64_e32 v[80:81], v[4:5]
	v_mov_b64_e32 v[24:25], v[4:5]
	v_mov_b64_e32 v[88:89], v[4:5]
	v_mov_b64_e32 v[32:33], v[4:5]
	v_mov_b64_e32 v[96:97], v[4:5]
	v_mov_b64_e32 v[36:37], v[4:5]
	v_mov_b64_e32 v[100:101], v[4:5]
	v_mov_b64_e32 v[44:45], v[4:5]
	v_mov_b64_e32 v[108:109], v[4:5]
	v_mov_b64_e32 v[52:53], v[4:5]
	v_mov_b64_e32 v[116:117], v[4:5]
	v_mov_b64_e32 v[60:61], v[4:5]
	v_mov_b64_e32 v[124:125], v[4:5]
	v_mov_b64_e32 v[40:41], v[4:5]
	v_mov_b64_e32 v[104:105], v[4:5]
	v_mov_b64_e32 v[48:49], v[4:5]
	v_mov_b64_e32 v[112:113], v[4:5]
	v_mov_b64_e32 v[56:57], v[4:5]
	v_mov_b64_e32 v[120:121], v[4:5]
	v_mov_b64_e32 v[64:65], v[4:5]
	v_mov_b64_e32 v[128:129], v[4:5]
	s_cselect_b32 s7, s92, s46
	s_cselect_b32 s30, s5, s47
	s_add_i32 s31, s46, 0x40080
	s_add_i32 s46, s47, 0x100
	s_mov_b32 s47, 0
	v_mov_b64_e32 v[66:67], v[2:3]
	v_mov_b64_e32 v[10:11], v[2:3]
	v_mov_b64_e32 v[74:75], v[2:3]
	v_mov_b64_e32 v[18:19], v[2:3]
	v_mov_b64_e32 v[82:83], v[2:3]
	v_mov_b64_e32 v[26:27], v[2:3]
	v_mov_b64_e32 v[90:91], v[2:3]
	v_mov_b64_e32 v[6:7], v[2:3]
	v_mov_b64_e32 v[70:71], v[2:3]
	v_mov_b64_e32 v[14:15], v[2:3]
	v_mov_b64_e32 v[78:79], v[2:3]
	v_mov_b64_e32 v[22:23], v[2:3]
	v_mov_b64_e32 v[86:87], v[2:3]
	v_mov_b64_e32 v[30:31], v[2:3]
	v_mov_b64_e32 v[94:95], v[2:3]
	v_mov_b64_e32 v[34:35], v[2:3]
	v_mov_b64_e32 v[98:99], v[2:3]
	v_mov_b64_e32 v[42:43], v[2:3]
	v_mov_b64_e32 v[106:107], v[2:3]
	v_mov_b64_e32 v[50:51], v[2:3]
	v_mov_b64_e32 v[114:115], v[2:3]
	v_mov_b64_e32 v[58:59], v[2:3]
	v_mov_b64_e32 v[122:123], v[2:3]
	v_mov_b64_e32 v[38:39], v[2:3]
	v_mov_b64_e32 v[102:103], v[2:3]
	v_mov_b64_e32 v[46:47], v[2:3]
	v_mov_b64_e32 v[110:111], v[2:3]
	v_mov_b64_e32 v[54:55], v[2:3]
	v_mov_b64_e32 v[118:119], v[2:3]
	v_mov_b64_e32 v[62:63], v[2:3]
	v_mov_b64_e32 v[126:127], v[2:3]
	.p2align	6

;     ...
;         bool has_next; if constexpr (QV == 2) has_next = S.next_tail(ui + 1, nxt); else has_next = S.next(ui + 1, nxt);
;         const unsigned nA = has_next ? (unsigned)nxt.pm * tstepA + nxt.aoff : cA, nB = has_next ? (unsigned)nxt.pn * tstepB + nxt.boff : cB;
;         if constexpr (QV == 0) {
; #pragma nounroll
;         for (int t = 0; t < nt; t += 2) {
;             const bool last = (t == nt - 2);
;             const unsigned a1 = cA + (unsigned)(t + 1) * kstep;
;             const unsigned a2 = last ? nA : cA + (unsigned)(t + 2) * kstep, b2 = last ? nB : cB + (unsigned)(t + 2) * kstep;
;             const unsigned a3 = a2 + kstep, b3 = b2 + kstep;
;     ...
;         if (!cur.keep) {
; #pragma unroll
;             for (int a = 0; a < 2; ++a)
; #pragma unroll
;                 for (int b = 0; b < 2; ++b)
; #pragma unroll
;                     for (int m = 0; m < 4; ++m)
; #pragma unroll
;                         for (int n = 0; n < 2; ++n) { f32x2 z0, z1; asm("v_mov_b64 %0, 0\n\tv_mov_b64 %1, 0" : "=v"(z0), "=v"(z1));
;                     acc[a][b][m][n] = __builtin_shufflevector(z0, z1, 0, 1, 2, 3); }
.LBB0_1273:
	s_lshl_b32 s65, s64, 20
	s_and_b64 s[30:31], s[38:39], exec
	s_cselect_b32 s30, s65, s62
	s_lshl_b32 s66, s59, 20
	s_and_b64 s[42:43], s[38:39], exec
	v_mov_b64_e32 v[8:9], v[4:5]
	v_mov_b64_e32 v[12:13], v[4:5]
	v_mov_b64_e32 v[16:17], v[4:5]
	v_mov_b64_e32 v[20:21], v[4:5]
	v_mov_b64_e32 v[24:25], v[4:5]
	s_waitcnt vmcnt(15)
	v_mov_b64_e32 v[28:29], v[4:5]
	v_mov_b64_e32 v[32:33], v[4:5]
	v_mov_b64_e32 v[68:69], v[4:5]
	v_mov_b64_e32 v[72:73], v[4:5]
	v_mov_b64_e32 v[76:77], v[4:5]
	v_mov_b64_e32 v[80:81], v[4:5]
	v_mov_b64_e32 v[84:85], v[4:5]
	v_mov_b64_e32 v[88:89], v[4:5]
	v_mov_b64_e32 v[92:93], v[4:5]
	v_mov_b64_e32 v[96:97], v[4:5]
	v_mov_b64_e32 v[36:37], v[4:5]
	v_mov_b64_e32 v[40:41], v[4:5]
	v_mov_b64_e32 v[44:45], v[4:5]
	v_mov_b64_e32 v[48:49], v[4:5]
	v_mov_b64_e32 v[52:53], v[4:5]
	v_mov_b64_e32 v[56:57], v[4:5]
	v_mov_b64_e32 v[60:61], v[4:5]
	v_mov_b64_e32 v[64:65], v[4:5]
	v_mov_b64_e32 v[100:101], v[4:5]
	v_mov_b64_e32 v[104:105], v[4:5]
	v_mov_b64_e32 v[108:109], v[4:5]
	v_mov_b64_e32 v[112:113], v[4:5]
	v_mov_b64_e32 v[116:117], v[4:5]
	v_mov_b64_e32 v[120:121], v[4:5]
	v_mov_b64_e32 v[124:125], v[4:5]
	v_mov_b64_e32 v[128:129], v[4:5]
	s_cselect_b32 s31, s66, s63
	s_add_i32 s62, s62, 0x80080
	s_addk_i32 s63, 0x100
	s_mov_b32 s67, -2
	v_mov_b64_e32 v[6:7], v[2:3]
	v_mov_b64_e32 v[10:11], v[2:3]
	v_mov_b64_e32 v[14:15], v[2:3]
	v_mov_b64_e32 v[18:19], v[2:3]
	v_mov_b64_e32 v[22:23], v[2:3]
	v_mov_b64_e32 v[26:27], v[2:3]
	v_mov_b64_e32 v[30:31], v[2:3]
	v_mov_b64_e32 v[66:67], v[2:3]
	v_mov_b64_e32 v[70:71], v[2:3]
	v_mov_b64_e32 v[74:75], v[2:3]
	v_mov_b64_e32 v[78:79], v[2:3]
	v_mov_b64_e32 v[82:83], v[2:3]
	v_mov_b64_e32 v[86:87], v[2:3]
	v_mov_b64_e32 v[90:91], v[2:3]
	v_mov_b64_e32 v[94:95], v[2:3]
	v_mov_b64_e32 v[34:35], v[2:3]
	v_mov_b64_e32 v[38:39], v[2:3]
	v_mov_b64_e32 v[42:43], v[2:3]
	v_mov_b64_e32 v[46:47], v[2:3]
	v_mov_b64_e32 v[50:51], v[2:3]
	v_mov_b64_e32 v[54:55], v[2:3]
	v_mov_b64_e32 v[58:59], v[2:3]
	v_mov_b64_e32 v[62:63], v[2:3]
	v_mov_b64_e32 v[98:99], v[2:3]
	v_mov_b64_e32 v[102:103], v[2:3]
	v_mov_b64_e32 v[106:107], v[2:3]
	v_mov_b64_e32 v[110:111], v[2:3]
	v_mov_b64_e32 v[114:115], v[2:3]
	v_mov_b64_e32 v[118:119], v[2:3]
	v_mov_b64_e32 v[122:123], v[2:3]
	v_mov_b64_e32 v[126:127], v[2:3]
	.p2align	6

; #define PG8_STAGEX(rs, bufoff, soff, voff) do { _Pragma("unroll") for (int _i = 0; _i < 2; ++_i) \
;         __builtin_amdgcn_raw_ptr_buffer_load_lds(rs, (LAS unsigned*)(lds + (bufoff) + ldsw + _i * 8192), 16, (voff)[_i], (soff), 0, 0); } while (0)
; #define PG8_WAIT_V(n) asm volatile("s_waitcnt vmcnt(" #n ")" ::: "memory")
; #define PG8_BAR __builtin_amdgcn_s_barrier()
;     ...
;     const int aoff = lds_byte(wr * 64 + fr, fq * 8), boff = lds_byte(wc * 32 + fr, fq * 8);
;     ...
;     Unit cur, nxt; int ui = 0;
;     if constexpr (QV == 2) { if (!S.next_tail(0, cur)) return; } else { if (!S.next(0, cur)) return; }
;     f32x4 acc[2][2][4][2];
; #pragma unroll
;     for (int a = 0; a < 2; ++a)
; #pragma unroll
;         for (int b = 0; b < 2; ++b)
; #pragma unroll
;             for (int m = 0; m < 4; ++m)
; #pragma unroll
;                 for (int n = 0; n < 2; ++n) { f32x2 z0, z1; asm("v_mov_b64 %0, 0\n\tv_mov_b64 %1, 0" : "=v"(z0), "=v"(z1));
;                     acc[a][b][m][n] = __builtin_shufflevector(z0, z1, 0, 1, 2, 3); }
;     bf16x8 At[4][2], B0[2][2], B1[2][2];
;     unsigned cA = (unsigned)cur.pm * tstepA + cur.aoff, cB = (unsigned)cur.pn * tstepB + cur.boff;
;     PG8_STAGEX(rsB, PG8_SB(0, 0), cB, voffB); PG8_STAGEX(rsB, PG8_SB(0, 1), cB + hstepB, voffB); PG8_STAGEX(rsA, PG8_SA(0, 0), cA, voffA); PG8_STAGEX(rsA, PG8_SA(0, 1), cA + hstepA, voffA);
;     if (wr == 1) PG8_BAR;
;     PG8_WAIT_V(2); PG8_BAR;
;     PG8_STAGEX(rsB, PG8_SB(1, 0), cB + kstep, voffB); PG8_STAGEX(rsA, PG8_SA(1, 0), cA + kstep, voffA); PG8_STAGEX(rsB, PG8_SB(1, 1), cB + hstepB + kstep, voffB);
;     PG8_WAIT_V(6); PG8_BAR;
.LBB0_1286:
	v_lshrrev_b32_e32 v7, 1, v162
	v_and_b32_e32 v71, 24, v7
	v_and_b32_e32 v6, 15, v162
	v_lshlrev_b32_e32 v7, 1, v71
	v_lshl_or_b32 v70, s21, 6, v6
	v_lshl_or_b32 v6, v6, 6, v7
	v_lshlrev_b32_e32 v7, 2, v162
	s_lshl_b32 s21, s21, 13
	v_and_b32_e32 v7, 32, v7
	v_bitop3_b32 v8, v6, s21, v7 bitop3:0xde
	s_lshl_b32 s21, s22, 5
	s_and_b32 s21, s21, 0x60
	s_lshl_b32 s22, s21, 7
	v_bitop3_b32 v6, s22, v6, v7 bitop3:0xf6
	s_add_i32 s22, s14, 0x18000
	s_or_b32 s24, s13, 0x80
	s_mov_b32 m0, s22
	s_add_i32 s23, s14, 0x1a000
	s_waitcnt vmcnt(2)
	s_barrier
	buffer_load_dwordx4 v67, s[40:43], s24 offen lds
	s_mov_b32 m0, s23
	s_or_b32 s26, s19, 0x80
	buffer_load_dwordx4 v69, s[40:43], s24 offen lds
	s_add_i32 s24, s14, 0x8000
	s_mov_b32 m0, s24
	s_add_i32 s25, s14, 0xa000
	buffer_load_dwordx4 v66, s[76:79], s26 offen lds
	s_mov_b32 m0, s25
	s_or_b32 s28, s13, 0x80080
	buffer_load_dwordx4 v68, s[76:79], s26 offen lds
	s_add_i32 s26, s14, 0x1c000
	s_mov_b32 m0, s26
	s_add_i32 s27, s14, 0x1e000
	buffer_load_dwordx4 v67, s[40:43], s28 offen lds
	s_mov_b32 m0, s27
	s_mov_b32 s29, -2
	buffer_load_dwordx4 v69, s[40:43], s28 offen lds
	s_waitcnt vmcnt(6)
	s_movk_i32 s28, 0x100
	v_add_u32_e32 v72, 0, v6
	v_add_u32_e32 v73, 0, v8
	v_mov_b32_e32 v6, v2
	v_mov_b32_e32 v7, v3
	v_mov_b32_e32 v8, v4
	v_mov_b32_e32 v9, v5
	v_mov_b32_e32 v10, v2
	v_mov_b32_e32 v11, v3
	v_mov_b32_e32 v12, v4
	v_mov_b32_e32 v13, v5
	v_mov_b32_e32 v14, v2
	v_mov_b32_e32 v15, v3
	v_mov_b32_e32 v16, v4
	v_mov_b32_e32 v17, v5
	v_mov_b32_e32 v18, v2
	v_mov_b32_e32 v19, v3
	v_mov_b32_e32 v20, v4
	v_mov_b32_e32 v21, v5
	v_mov_b32_e32 v22, v2
	v_mov_b32_e32 v23, v3
	v_mov_b32_e32 v24, v4
	v_mov_b32_e32 v25, v5
	s_waitcnt vmcnt(15)
	v_mov_b32_e32 v26, v2
	v_mov_b32_e32 v27, v3
	v_mov_b32_e32 v28, v4
	v_mov_b32_e32 v29, v5
	v_mov_b32_e32 v30, v2
	v_mov_b32_e32 v31, v3
	v_mov_b32_e32 v32, v4
	v_mov_b32_e32 v33, v5
	v_mov_b32_e32 v34, v2
	v_mov_b32_e32 v35, v3
	v_mov_b32_e32 v36, v4
	v_mov_b32_e32 v37, v5
	v_mov_b32_e32 v38, v2
	v_mov_b32_e32 v39, v3
	v_mov_b32_e32 v40, v4
	v_mov_b32_e32 v41, v5
	v_mov_b32_e32 v42, v2
	v_mov_b32_e32 v43, v3
	v_mov_b32_e32 v44, v4
	v_mov_b32_e32 v45, v5
	v_mov_b32_e32 v46, v2
	v_mov_b32_e32 v47, v3
	v_mov_b32_e32 v48, v4
	v_mov_b32_e32 v49, v5
	v_mov_b32_e32 v50, v2
	v_mov_b32_e32 v51, v3
	v_mov_b32_e32 v52, v4
	v_mov_b32_e32 v53, v5
	v_mov_b32_e32 v54, v2
	v_mov_b32_e32 v55, v3
	v_mov_b32_e32 v56, v4
	v_mov_b32_e32 v57, v5
	v_mov_b32_e32 v58, v2
	v_mov_b32_e32 v59, v3
	v_mov_b32_e32 v60, v4
	v_mov_b32_e32 v61, v5
	v_mov_b32_e32 v62, v2
	v_mov_b32_e32 v63, v3
	v_mov_b32_e32 v64, v4
	v_mov_b32_e32 v65, v5
	s_barrier
	.p2align	6

;     ...
;         bool has_next; if constexpr (QV == 2) has_next = S.next_tail(ui + 1, nxt); else has_next = S.next(ui + 1, nxt);
;         const unsigned nA = has_next ? (unsigned)nxt.pm * tstepA + nxt.aoff : cA, nB = has_next ? (unsigned)nxt.pn * tstepB + nxt.boff : cB;
;         if constexpr (QV == 0) {
; #pragma nounroll
;         for (int t = 0; t < nt; t += 2) {
;             const bool last = (t == nt - 2);
;             const unsigned a1 = cA + (unsigned)(t + 1) * kstep;
;             const unsigned a2 = last ? nA : cA + (unsigned)(t + 2) * kstep, b2 = last ? nB : cB + (unsigned)(t + 2) * kstep;
;             const unsigned a3 = a2 + kstep, b3 = b2 + kstep;
.LBB0_1376:
	s_mul_i32 s55, s54, 0x180000
	s_add_i32 s55, s55, s29
	s_and_b64 s[30:31], s[38:39], exec
	s_cselect_b32 s30, s55, s43
	s_lshl_b32 s58, s26, 19
	s_add_i32 s58, s58, s28
	s_and_b64 s[50:51], s[38:39], exec
	s_cselect_b32 s31, s58, s59
	s_add_i32 s43, s43, 0xc0080
	s_addk_i32 s59, 0x100
	s_mov_b32 s60, -2
	.p2align	6

;     ...
;         bool has_next; if constexpr (QV == 2) has_next = S.next_tail(ui + 1, nxt); else has_next = S.next(ui + 1, nxt);
;         const unsigned nA = has_next ? (unsigned)nxt.pm * tstepA + nxt.aoff : cA, nB = has_next ? (unsigned)nxt.pn * tstepB + nxt.boff : cB;
;         if constexpr (QV == 0) {
; #pragma nounroll
;         for (int t = 0; t < nt; t += 2) {
;             const bool last = (t == nt - 2);
;             const unsigned a1 = cA + (unsigned)(t + 1) * kstep;
;             const unsigned a2 = last ? nA : cA + (unsigned)(t + 2) * kstep, b2 = last ? nB : cB + (unsigned)(t + 2) * kstep;
;             const unsigned a3 = a2 + kstep, b3 = b2 + kstep;
.LBB0_1428:
	s_mul_i32 s24, s1, 0x180000
	s_add_i32 s24, s24, s22
	s_and_b64 s[46:47], s[30:31], exec
	s_cselect_b32 s38, s24, s40
	s_lshl_b32 s25, s2, 19
	s_add_i32 s25, s25, s21
	s_and_b64 s[30:31], s[30:31], exec
	s_cselect_b32 s30, s25, s39
	s_add_i32 s31, s39, 0x100
	s_add_i32 s39, s40, 0x100
	s_mov_b32 s40, -2
	.p2align	6

;     ...
;         bool has_next; if constexpr (QV == 2) has_next = S.next_tail(ui + 1, nxt); else has_next = S.next(ui + 1, nxt);
;         const unsigned nA = has_next ? (unsigned)nxt.pm * tstepA + nxt.aoff : cA, nB = has_next ? (unsigned)nxt.pn * tstepB + nxt.boff : cB;
;         if constexpr (QV == 0) {
; #pragma nounroll
;         for (int t = 0; t < nt; t += 2) {
;             const bool last = (t == nt - 2);
;             const unsigned a1 = cA + (unsigned)(t + 1) * kstep;
;             const unsigned a2 = last ? nA : cA + (unsigned)(t + 2) * kstep, b2 = last ? nB : cB + (unsigned)(t + 2) * kstep;
;             const unsigned a3 = a2 + kstep, b3 = b2 + kstep;
;     ...
;         if (!cur.keep) {
; #pragma unroll
;             for (int a = 0; a < 2; ++a)
; #pragma unroll
;                 for (int b = 0; b < 2; ++b)
; #pragma unroll
;                     for (int m = 0; m < 4; ++m)
; #pragma unroll
;                         for (int n = 0; n < 2; ++n) { f32x2 z0, z1; asm("v_mov_b64 %0, 0\n\tv_mov_b64 %1, 0" : "=v"(z0), "=v"(z1));
;                     acc[a][b][m][n] = __builtin_shufflevector(z0, z1, 0, 1, 2, 3); }
.LBB0_1528:
	s_lshl_b32 s86, s65, 20
	s_and_b64 s[30:31], s[60:61], exec
	s_cselect_b32 s30, s86, s59
	s_lshl_b32 s87, s47, 20
	s_mov_b32 s84, s47
	s_and_b64 s[46:47], s[60:61], exec
	s_waitcnt lgkmcnt(0)
	v_mov_b64_e32 v[8:9], v[4:5]
	v_mov_b64_e32 v[12:13], v[4:5]
	v_mov_b64_e32 v[16:17], v[4:5]
	v_mov_b64_e32 v[20:21], v[4:5]
	v_mov_b64_e32 v[24:25], v[4:5]
	s_waitcnt vmcnt(15)
	v_mov_b64_e32 v[28:29], v[4:5]
	v_mov_b64_e32 v[32:33], v[4:5]
	v_mov_b64_e32 v[68:69], v[4:5]
	v_mov_b64_e32 v[72:73], v[4:5]
	v_mov_b64_e32 v[76:77], v[4:5]
	v_mov_b64_e32 v[80:81], v[4:5]
	v_mov_b64_e32 v[84:85], v[4:5]
	v_mov_b64_e32 v[88:89], v[4:5]
	v_mov_b64_e32 v[92:93], v[4:5]
	v_mov_b64_e32 v[96:97], v[4:5]
	v_mov_b64_e32 v[36:37], v[4:5]
	v_mov_b64_e32 v[40:41], v[4:5]
	v_mov_b64_e32 v[44:45], v[4:5]
	v_mov_b64_e32 v[48:49], v[4:5]
	v_mov_b64_e32 v[52:53], v[4:5]
	v_mov_b64_e32 v[56:57], v[4:5]
	v_mov_b64_e32 v[60:61], v[4:5]
	v_mov_b64_e32 v[64:65], v[4:5]
	v_mov_b64_e32 v[100:101], v[4:5]
	v_mov_b64_e32 v[104:105], v[4:5]
	v_mov_b64_e32 v[136:137], v[4:5]
	v_mov_b64_e32 v[140:141], v[4:5]
	v_mov_b64_e32 v[148:149], v[4:5]
	v_mov_b64_e32 v[152:153], v[4:5]
	v_mov_b64_e32 v[156:157], v[4:5]
	v_mov_b64_e32 v[160:161], v[4:5]
	s_mov_b32 s85, s65
	s_cselect_b32 s31, s87, s63
	s_add_i32 s59, s59, 0x80080
	s_addk_i32 s63, 0x100
	s_mov_b32 s64, -2
	v_mov_b64_e32 v[6:7], v[2:3]
	v_mov_b64_e32 v[10:11], v[2:3]
	v_mov_b64_e32 v[14:15], v[2:3]
	v_mov_b64_e32 v[18:19], v[2:3]
	v_mov_b64_e32 v[22:23], v[2:3]
	v_mov_b64_e32 v[26:27], v[2:3]
	v_mov_b64_e32 v[30:31], v[2:3]
	v_mov_b64_e32 v[66:67], v[2:3]
	v_mov_b64_e32 v[70:71], v[2:3]
	v_mov_b64_e32 v[74:75], v[2:3]
	v_mov_b64_e32 v[78:79], v[2:3]
	v_mov_b64_e32 v[82:83], v[2:3]
	v_mov_b64_e32 v[86:87], v[2:3]
	v_mov_b64_e32 v[90:91], v[2:3]
	v_mov_b64_e32 v[94:95], v[2:3]
	v_mov_b64_e32 v[34:35], v[2:3]
	v_mov_b64_e32 v[38:39], v[2:3]
	v_mov_b64_e32 v[42:43], v[2:3]
	v_mov_b64_e32 v[46:47], v[2:3]
	v_mov_b64_e32 v[50:51], v[2:3]
	v_mov_b64_e32 v[54:55], v[2:3]
	v_mov_b64_e32 v[58:59], v[2:3]
	v_mov_b64_e32 v[62:63], v[2:3]
	v_mov_b64_e32 v[98:99], v[2:3]
	v_mov_b64_e32 v[102:103], v[2:3]
	v_mov_b64_e32 v[134:135], v[2:3]
	v_mov_b64_e32 v[138:139], v[2:3]
	v_mov_b64_e32 v[146:147], v[2:3]
	v_mov_b64_e32 v[150:151], v[2:3]
	v_mov_b64_e32 v[154:155], v[2:3]
	v_mov_b64_e32 v[158:159], v[2:3]
	.p2align	6

;     ...
;         bool has_next; if constexpr (QV == 2) has_next = S.next_tail(ui + 1, nxt); else has_next = S.next(ui + 1, nxt);
;         const unsigned nA = has_next ? (unsigned)nxt.pm * tstepA + nxt.aoff : cA, nB = has_next ? (unsigned)nxt.pn * tstepB + nxt.boff : cB;
;         if constexpr (QV == 0) {
; #pragma nounroll
;         for (int t = 0; t < nt; t += 2) {
;             const bool last = (t == nt - 2);
;             const unsigned a1 = cA + (unsigned)(t + 1) * kstep;
;             const unsigned a2 = last ? nA : cA + (unsigned)(t + 2) * kstep, b2 = last ? nB : cB + (unsigned)(t + 2) * kstep;
;             const unsigned a3 = a2 + kstep, b3 = b2 + kstep;
;     ...
;         if (!cur.keep) {
; #pragma unroll
;             for (int a = 0; a < 2; ++a)
; #pragma unroll
;                 for (int b = 0; b < 2; ++b)
; #pragma unroll
;                     for (int m = 0; m < 4; ++m)
; #pragma unroll
;                         for (int n = 0; n < 2; ++n) { f32x2 z0, z1; asm("v_mov_b64 %0, 0\n\tv_mov_b64 %1, 0" : "=v"(z0), "=v"(z1));
;                     acc[a][b][m][n] = __builtin_shufflevector(z0, z1, 0, 1, 2, 3); }
.LBB0_1650:
	s_lshl_b32 s55, s54, 20
	s_and_b64 s[30:31], s[38:39], exec
	s_cselect_b32 s30, s55, s61
	s_lshl_b32 s58, s53, 20
	s_and_b64 s[42:43], s[38:39], exec
	v_mov_b64_e32 v[12:13], v[4:5]
	v_mov_b64_e32 v[20:21], v[4:5]
	s_waitcnt vmcnt(15)
	v_mov_b64_e32 v[28:29], v[4:5]
	v_mov_b64_e32 v[36:37], v[4:5]
	v_mov_b64_e32 v[44:45], v[4:5]
	v_mov_b64_e32 v[52:53], v[4:5]
	v_mov_b64_e32 v[60:61], v[4:5]
	v_mov_b64_e32 v[8:9], v[4:5]
	v_mov_b64_e32 v[16:17], v[4:5]
	v_mov_b64_e32 v[24:25], v[4:5]
	v_mov_b64_e32 v[32:33], v[4:5]
	v_mov_b64_e32 v[40:41], v[4:5]
	v_mov_b64_e32 v[48:49], v[4:5]
	v_mov_b64_e32 v[56:57], v[4:5]
	v_mov_b64_e32 v[64:65], v[4:5]
	v_mov_b64_e32 v[68:69], v[4:5]
	v_mov_b64_e32 v[76:77], v[4:5]
	v_mov_b64_e32 v[92:93], v[4:5]
	v_mov_b64_e32 v[108:109], v[4:5]
	v_mov_b64_e32 v[116:117], v[4:5]
	v_mov_b64_e32 v[124:125], v[4:5]
	v_mov_b64_e32 v[132:133], v[4:5]
	v_mov_b64_e32 v[140:141], v[4:5]
	v_mov_b64_e32 v[72:73], v[4:5]
	v_mov_b64_e32 v[80:81], v[4:5]
	v_mov_b64_e32 v[96:97], v[4:5]
	v_mov_b64_e32 v[112:113], v[4:5]
	v_mov_b64_e32 v[120:121], v[4:5]
	v_mov_b64_e32 v[128:129], v[4:5]
	v_mov_b64_e32 v[136:137], v[4:5]
	v_mov_b64_e32 v[144:145], v[4:5]
	s_cselect_b32 s31, s58, s62
	s_add_i32 s61, s61, 0x80080
	s_addk_i32 s62, 0x100
	s_mov_b32 s63, -2
	v_mov_b64_e32 v[10:11], v[2:3]
	v_mov_b64_e32 v[18:19], v[2:3]
	v_mov_b64_e32 v[26:27], v[2:3]
	v_mov_b64_e32 v[34:35], v[2:3]
	v_mov_b64_e32 v[42:43], v[2:3]
	v_mov_b64_e32 v[50:51], v[2:3]
	v_mov_b64_e32 v[58:59], v[2:3]
	v_mov_b64_e32 v[6:7], v[2:3]
	v_mov_b64_e32 v[14:15], v[2:3]
	v_mov_b64_e32 v[22:23], v[2:3]
	v_mov_b64_e32 v[30:31], v[2:3]
	v_mov_b64_e32 v[38:39], v[2:3]
	v_mov_b64_e32 v[46:47], v[2:3]
	v_mov_b64_e32 v[54:55], v[2:3]
	v_mov_b64_e32 v[62:63], v[2:3]
	v_mov_b64_e32 v[66:67], v[2:3]
	v_mov_b64_e32 v[74:75], v[2:3]
	v_mov_b64_e32 v[90:91], v[2:3]
	v_mov_b64_e32 v[106:107], v[2:3]
	v_mov_b64_e32 v[114:115], v[2:3]
	v_mov_b64_e32 v[122:123], v[2:3]
	v_mov_b64_e32 v[130:131], v[2:3]
	v_mov_b64_e32 v[138:139], v[2:3]
	v_mov_b64_e32 v[70:71], v[2:3]
	v_mov_b64_e32 v[78:79], v[2:3]
	v_mov_b64_e32 v[94:95], v[2:3]
	v_mov_b64_e32 v[110:111], v[2:3]
	v_mov_b64_e32 v[118:119], v[2:3]
	v_mov_b64_e32 v[126:127], v[2:3]
	v_mov_b64_e32 v[134:135], v[2:3]
	v_mov_b64_e32 v[142:143], v[2:3]
	.p2align	6

; #define PG8_STAGEX(rs, bufoff, soff, voff) do { _Pragma("unroll") for (int _i = 0; _i < 2; ++_i) \
;         __builtin_amdgcn_raw_ptr_buffer_load_lds(rs, (LAS unsigned*)(lds + (bufoff) + ldsw + _i * 8192), 16, (voff)[_i], (soff), 0, 0); } while (0)
; #define PG8_WAIT_V(n) asm volatile("s_waitcnt vmcnt(" #n ")" ::: "memory")
; #define PG8_BAR __builtin_amdgcn_s_barrier()
;     ...
;     const int aoff = lds_byte(wr * 64 + fr, fq * 8), boff = lds_byte(wc * 32 + fr, fq * 8);
;     ...
;     Unit cur, nxt; int ui = 0;
;     if constexpr (QV == 2) { if (!S.next_tail(0, cur)) return; } else { if (!S.next(0, cur)) return; }
;     f32x4 acc[2][2][4][2];
; #pragma unroll
;     for (int a = 0; a < 2; ++a)
; #pragma unroll
;         for (int b = 0; b < 2; ++b)
; #pragma unroll
;             for (int m = 0; m < 4; ++m)
; #pragma unroll
;                 for (int n = 0; n < 2; ++n) { f32x2 z0, z1; asm("v_mov_b64 %0, 0\n\tv_mov_b64 %1, 0" : "=v"(z0), "=v"(z1));
;                     acc[a][b][m][n] = __builtin_shufflevector(z0, z1, 0, 1, 2, 3); }
;     bf16x8 At[4][2], B0[2][2], B1[2][2];
;     unsigned cA = (unsigned)cur.pm * tstepA + cur.aoff, cB = (unsigned)cur.pn * tstepB + cur.boff;
;     PG8_STAGEX(rsB, PG8_SB(0, 0), cB, voffB); PG8_STAGEX(rsB, PG8_SB(0, 1), cB + hstepB, voffB); PG8_STAGEX(rsA, PG8_SA(0, 0), cA, voffA); PG8_STAGEX(rsA, PG8_SA(0, 1), cA + hstepA, voffA);
;     if (wr == 1) PG8_BAR;
;     PG8_WAIT_V(2); PG8_BAR;
;     PG8_STAGEX(rsB, PG8_SB(1, 0), cB + kstep, voffB); PG8_STAGEX(rsA, PG8_SA(1, 0), cA + kstep, voffA); PG8_STAGEX(rsB, PG8_SB(1, 1), cB + hstepB + kstep, voffB);
;     PG8_WAIT_V(6); PG8_BAR;
.LBB0_1667:
	v_lshrrev_b32_e32 v7, 1, v149
	v_and_b32_e32 v71, 24, v7
	v_and_b32_e32 v6, 15, v149
	v_lshlrev_b32_e32 v7, 1, v71
	v_lshl_or_b32 v70, s19, 6, v6
	v_lshl_or_b32 v6, v6, 6, v7
	v_lshlrev_b32_e32 v7, 2, v149
	s_lshl_b32 s19, s19, 13
	v_and_b32_e32 v7, 32, v7
	v_bitop3_b32 v8, v6, s19, v7 bitop3:0xde
	s_lshl_b32 s19, s20, 5
	s_and_b32 s19, s19, 0x60
	s_lshl_b32 s20, s19, 7
	v_bitop3_b32 v6, s20, v6, v7 bitop3:0xf6
	s_add_i32 s20, s12, 0x18000
	s_or_b32 s22, s10, 0x80
	s_mov_b32 m0, s20
	s_add_i32 s21, s12, 0x1a000
	s_waitcnt vmcnt(2)
	s_barrier
	buffer_load_dwordx4 v67, s[40:43], s22 offen lds
	s_mov_b32 m0, s21
	s_or_b32 s24, s17, 0x80
	buffer_load_dwordx4 v69, s[40:43], s22 offen lds
	s_add_i32 s22, s12, 0x8000
	s_mov_b32 m0, s22
	s_add_i32 s23, s12, 0xa000
	buffer_load_dwordx4 v66, s[76:79], s24 offen lds
	s_mov_b32 m0, s23
	s_or_b32 s26, s10, 0x80080
	buffer_load_dwordx4 v68, s[76:79], s24 offen lds
	s_add_i32 s24, s12, 0x1c000
	s_mov_b32 m0, s24
	s_add_i32 s25, s12, 0x1e000
	buffer_load_dwordx4 v67, s[40:43], s26 offen lds
	s_mov_b32 m0, s25
	s_mov_b32 s27, -2
	buffer_load_dwordx4 v69, s[40:43], s26 offen lds
	s_waitcnt vmcnt(6)
	s_movk_i32 s26, 0x100
	v_add_u32_e32 v72, 0, v6
	v_add_u32_e32 v73, 0, v8
	v_mov_b32_e32 v10, v2
	v_mov_b32_e32 v11, v3
	v_mov_b32_e32 v12, v4
	v_mov_b32_e32 v13, v5
	v_mov_b32_e32 v18, v2
	v_mov_b32_e32 v19, v3
	v_mov_b32_e32 v20, v4
	v_mov_b32_e32 v21, v5
	s_waitcnt vmcnt(15)
	v_mov_b32_e32 v26, v2
	v_mov_b32_e32 v27, v3
	v_mov_b32_e32 v28, v4
	v_mov_b32_e32 v29, v5
	v_mov_b32_e32 v34, v2
	v_mov_b32_e32 v35, v3
	v_mov_b32_e32 v36, v4
	v_mov_b32_e32 v37, v5
	v_mov_b32_e32 v42, v2
	v_mov_b32_e32 v43, v3
	v_mov_b32_e32 v44, v4
	v_mov_b32_e32 v45, v5
	v_mov_b32_e32 v46, v2
	v_mov_b32_e32 v47, v3
	v_mov_b32_e32 v48, v4
	v_mov_b32_e32 v49, v5
	v_mov_b32_e32 v50, v2
	v_mov_b32_e32 v51, v3
	v_mov_b32_e32 v52, v4
	v_mov_b32_e32 v53, v5
	v_mov_b32_e32 v6, v2
	v_mov_b32_e32 v7, v3
	v_mov_b32_e32 v8, v4
	v_mov_b32_e32 v9, v5
	v_mov_b32_e32 v14, v2
	v_mov_b32_e32 v15, v3
	v_mov_b32_e32 v16, v4
	v_mov_b32_e32 v17, v5
	v_mov_b32_e32 v22, v2
	v_mov_b32_e32 v23, v3
	v_mov_b32_e32 v24, v4
	v_mov_b32_e32 v25, v5
	v_mov_b32_e32 v30, v2
	v_mov_b32_e32 v31, v3
	v_mov_b32_e32 v32, v4
	v_mov_b32_e32 v33, v5
	v_mov_b32_e32 v38, v2
	v_mov_b32_e32 v39, v3
	v_mov_b32_e32 v40, v4
	v_mov_b32_e32 v41, v5
	v_mov_b32_e32 v54, v2
	v_mov_b32_e32 v55, v3
	v_mov_b32_e32 v56, v4
	v_mov_b32_e32 v57, v5
	v_mov_b32_e32 v58, v2
	v_mov_b32_e32 v59, v3
	v_mov_b32_e32 v60, v4
	v_mov_b32_e32 v61, v5
	v_mov_b32_e32 v62, v2
	v_mov_b32_e32 v63, v3
	v_mov_b32_e32 v64, v4
	v_mov_b32_e32 v65, v5
	s_barrier
	.p2align	6

;     ...
;         bool has_next; if constexpr (QV == 2) has_next = S.next_tail(ui + 1, nxt); else has_next = S.next(ui + 1, nxt);
;         const unsigned nA = has_next ? (unsigned)nxt.pm * tstepA + nxt.aoff : cA, nB = has_next ? (unsigned)nxt.pn * tstepB + nxt.boff : cB;
;         if constexpr (QV == 0) {
; #pragma nounroll
;         for (int t = 0; t < nt; t += 2) {
;             const bool last = (t == nt - 2);
;             const unsigned a1 = cA + (unsigned)(t + 1) * kstep;
;             const unsigned a2 = last ? nA : cA + (unsigned)(t + 2) * kstep, b2 = last ? nB : cB + (unsigned)(t + 2) * kstep;
;             const unsigned a3 = a2 + kstep, b3 = b2 + kstep;
;     ...
;         if (!cur.keep) {
; #pragma unroll
;             for (int a = 0; a < 2; ++a)
; #pragma unroll
;                 for (int b = 0; b < 2; ++b)
; #pragma unroll
;                     for (int m = 0; m < 4; ++m)
; #pragma unroll
;                         for (int n = 0; n < 2; ++n) { f32x2 z0, z1; asm("v_mov_b64 %0, 0\n\tv_mov_b64 %1, 0" : "=v"(z0), "=v"(z1));
;                     acc[a][b][m][n] = __builtin_shufflevector(z0, z1, 0, 1, 2, 3); }
.LBB0_1749:
	s_mul_i32 s84, s47, 0x2b0000
	s_and_b64 s[30:31], s[58:59], exec
	s_mul_i32 s85, s41, 0x2b0000
	s_waitcnt lgkmcnt(0)
	v_mov_b64_e32 v[8:9], v[4:5]
	v_mov_b64_e32 v[12:13], v[4:5]
	v_mov_b64_e32 v[16:17], v[4:5]
	v_mov_b64_e32 v[20:21], v[4:5]
	v_mov_b64_e32 v[24:25], v[4:5]
	s_waitcnt vmcnt(15)
	v_mov_b64_e32 v[28:29], v[4:5]
	v_mov_b64_e32 v[32:33], v[4:5]
	v_mov_b64_e32 v[68:69], v[4:5]
	v_mov_b64_e32 v[74:75], v[4:5]
	v_mov_b64_e32 v[80:81], v[4:5]
	v_mov_b64_e32 v[84:85], v[4:5]
	v_mov_b64_e32 v[88:89], v[4:5]
	v_mov_b64_e32 v[92:93], v[4:5]
	v_mov_b64_e32 v[96:97], v[4:5]
	v_mov_b64_e32 v[100:101], v[4:5]
	v_mov_b64_e32 v[36:37], v[4:5]
	v_mov_b64_e32 v[40:41], v[4:5]
	v_mov_b64_e32 v[44:45], v[4:5]
	v_mov_b64_e32 v[48:49], v[4:5]
	v_mov_b64_e32 v[52:53], v[4:5]
	v_mov_b64_e32 v[56:57], v[4:5]
	v_mov_b64_e32 v[60:61], v[4:5]
	v_mov_b64_e32 v[64:65], v[4:5]
	v_mov_b64_e32 v[104:105], v[4:5]
	v_mov_b64_e32 v[108:109], v[4:5]
	v_mov_b64_e32 v[112:113], v[4:5]
	v_mov_b64_e32 v[116:117], v[4:5]
	v_mov_b64_e32 v[120:121], v[4:5]
	v_mov_b64_e32 v[124:125], v[4:5]
	v_mov_b64_e32 v[128:129], v[4:5]
	v_mov_b64_e32 v[132:133], v[4:5]
	s_mov_b32 s83, s47
	s_mov_b32 s82, s41
	s_cselect_b32 s30, s84, s61
	s_cselect_b32 s31, s85, s60
	s_add_i32 s40, s61, 0x158080
	s_add_i32 s41, s60, 0x100
	s_mov_b32 s60, -2
	v_mov_b64_e32 v[6:7], v[2:3]
	v_mov_b64_e32 v[10:11], v[2:3]
	v_mov_b64_e32 v[14:15], v[2:3]
	v_mov_b64_e32 v[18:19], v[2:3]
	v_mov_b64_e32 v[22:23], v[2:3]
	v_mov_b64_e32 v[26:27], v[2:3]
	v_mov_b64_e32 v[30:31], v[2:3]
	v_mov_b64_e32 v[66:67], v[2:3]
	v_mov_b64_e32 v[72:73], v[2:3]
	v_mov_b64_e32 v[78:79], v[2:3]
	v_mov_b64_e32 v[82:83], v[2:3]
	v_mov_b64_e32 v[86:87], v[2:3]
	v_mov_b64_e32 v[90:91], v[2:3]
	v_mov_b64_e32 v[94:95], v[2:3]
	v_mov_b64_e32 v[98:99], v[2:3]
	v_mov_b64_e32 v[34:35], v[2:3]
	v_mov_b64_e32 v[38:39], v[2:3]
	v_mov_b64_e32 v[42:43], v[2:3]
	v_mov_b64_e32 v[46:47], v[2:3]
	v_mov_b64_e32 v[50:51], v[2:3]
	v_mov_b64_e32 v[54:55], v[2:3]
	v_mov_b64_e32 v[58:59], v[2:3]
	v_mov_b64_e32 v[62:63], v[2:3]
	v_mov_b64_e32 v[102:103], v[2:3]
	v_mov_b64_e32 v[106:107], v[2:3]
	v_mov_b64_e32 v[110:111], v[2:3]
	v_mov_b64_e32 v[114:115], v[2:3]
	v_mov_b64_e32 v[118:119], v[2:3]
	v_mov_b64_e32 v[122:123], v[2:3]
	v_mov_b64_e32 v[126:127], v[2:3]
	v_mov_b64_e32 v[130:131], v[2:3]
	.p2align	6
